# FoX layer0 and layer2 tile loops restructured like MoBA (all four attention loops: batched LDS reads, MFMAs before barrier1, softmax VALU between barriers)
# baseline (speedup 1.0000x reference)
; #define ATT_LAS __attribute__((address_space(3)))
; #define ATT_MFMA(a, b, c) __builtin_amdgcn_mfma_f32_32x32x16_bf16((a), (b), (c), 0, 0, 0)
; __device__ __forceinline__ void qkt(f32x16& p0, f32x16& p1, lds_cptr kb, const bf16x8* qr, const f32x16& z) {
; #pragma unroll
;     for (int d0 = 0; d0 < 4; ++d0) {
;         const bf16x8 b0 = *(const ATT_LAS bf16x8*)(kb + d0 * 2048);
;         const bf16x8 b1 = *(const ATT_LAS bf16x8*)(kb + d0 * 2048 + 512);
;         if (d0 == 0) { p0 = ATT_MFMA(b0, qr[0], z); p1 = ATT_MFMA(b1, qr[0], z); }
;         else { p0 = ATT_MFMA(b0, qr[d0], p0); p1 = ATT_MFMA(b1, qr[d0], p1); } }
; }
; __device__ __forceinline__ void pv(f32x16* o, int vb, bf16x8 pa0, bf16x8 pa1, bf16x8 pa2, bf16x8 pa3) {
; #pragma unroll
;     for (int d0 = 0; d0 < 2; ++d0) { s16x4 lo[4], hi[4];
; #pragma unroll
;         for (int ks = 0; ks < 4; ++ks) {
;             asm volatile("ds_read_b64_tr_b16 %0,%1 offset:%c2" : "=&v"(lo[ks]) : "v"(vb), "i"(d0 * 4096 + ks * 1024) : "memory");
;             asm volatile("ds_read_b64_tr_b16 %0,%1 offset:%c2" : "=&v"(hi[ks]) : "v"(vb), "i"(d0 * 4096 + ks * 1024 + 512) : "memory"); }
;         asm volatile("s_waitcnt lgkmcnt(0)" ::: "memory"); __builtin_amdgcn_sched_barrier(0);
;     ...
;         o[d0] = ATT_MFMA(pa0, ATT_PK(0), o[d0]);
;         o[d0] = ATT_MFMA(pa1, ATT_PK(1), o[d0]);
;         o[d0] = ATT_MFMA(pa2, ATT_PK(2), o[d0]);
;         o[d0] = ATT_MFMA(pa3, ATT_PK(3), o[d0]);
;     ...
;     }
; }
.LBB0_399:
	s_add_i32 s54, s6, 0x2000
	s_and_b32 s7, s54, 0x6000
	v_add_u32_e32 v60, s7, v129
	s_and_b32 s6, s6, 0x6000
	ds_read_b128 v[210:213], v60
	ds_read_b128 v[214:217], v60 offset:512
	ds_read_b128 v[218:221], v60 offset:2048
	ds_read_b128 v[222:225], v60 offset:2560
	ds_read_b128 v[226:229], v60 offset:4096
	ds_read_b128 v[230:233], v60 offset:4608
	ds_read_b128 v[234:237], v60 offset:6144
	ds_read_b128 v[238:241], v60 offset:6656
	v_add_u32_e32 v242, s6, v131
	ds_read_b64_tr_b16 v[178:179], v242
	ds_read_b64_tr_b16 v[180:181], v242 offset:512
	ds_read_b64_tr_b16 v[182:183], v242 offset:1024
	ds_read_b64_tr_b16 v[184:185], v242 offset:1536
	ds_read_b64_tr_b16 v[186:187], v242 offset:2048
	ds_read_b64_tr_b16 v[188:189], v242 offset:2560
	ds_read_b64_tr_b16 v[190:191], v242 offset:3072
	ds_read_b64_tr_b16 v[192:193], v242 offset:3584
	s_waitcnt lgkmcnt(14)
	v_mfma_f32_32x32x16_bf16 v[68:83], v[210:213], v[114:117], v[0:15]
	v_mfma_f32_32x32x16_bf16 v[86:101], v[214:217], v[114:117], v[0:15]
	s_waitcnt lgkmcnt(12)
	v_mfma_f32_32x32x16_bf16 v[68:83], v[218:221], v[110:113], v[68:83]
	v_mfma_f32_32x32x16_bf16 v[86:101], v[222:225], v[110:113], v[86:101]
	s_waitcnt lgkmcnt(10)
	v_mfma_f32_32x32x16_bf16 v[68:83], v[226:229], v[106:109], v[68:83]
	v_mfma_f32_32x32x16_bf16 v[86:101], v[230:233], v[106:109], v[86:101]
	s_waitcnt lgkmcnt(8)
	v_mfma_f32_32x32x16_bf16 v[68:83], v[234:237], v[102:105], v[68:83]
	v_mfma_f32_32x32x16_bf16 v[86:101], v[238:241], v[102:105], v[86:101]
	ds_read_b64_tr_b16 v[194:195], v242 offset:4096
	ds_read_b64_tr_b16 v[196:197], v242 offset:4608
	ds_read_b64_tr_b16 v[198:199], v242 offset:5120
	ds_read_b64_tr_b16 v[200:201], v242 offset:5632
	ds_read_b64_tr_b16 v[202:203], v242 offset:6144
	ds_read_b64_tr_b16 v[204:205], v242 offset:6656
	ds_read_b64_tr_b16 v[206:207], v242 offset:7168
	ds_read_b64_tr_b16 v[208:209], v242 offset:7680
	s_waitcnt lgkmcnt(14)
	v_mfma_f32_32x32x16_bf16 v[16:31], v[56:59], v[178:181], v[16:31]
	s_waitcnt lgkmcnt(12)
	v_mfma_f32_32x32x16_bf16 v[16:31], v[52:55], v[182:185], v[16:31]
	s_waitcnt lgkmcnt(10)
	v_mfma_f32_32x32x16_bf16 v[16:31], v[48:51], v[186:189], v[16:31]
	s_waitcnt lgkmcnt(8)
	v_mfma_f32_32x32x16_bf16 v[16:31], v[62:65], v[190:193], v[16:31]
	s_waitcnt lgkmcnt(6)
	v_mfma_f32_32x32x16_bf16 v[32:47], v[56:59], v[194:197], v[32:47]
	s_waitcnt lgkmcnt(4)
	v_mfma_f32_32x32x16_bf16 v[32:47], v[52:55], v[198:201], v[32:47]
	s_waitcnt lgkmcnt(2)
	v_mfma_f32_32x32x16_bf16 v[32:47], v[48:51], v[202:205], v[32:47]
	s_waitcnt lgkmcnt(0)
	v_mfma_f32_32x32x16_bf16 v[32:47], v[62:65], v[206:209], v[32:47]
	s_barrier
	ds_read_b128 v[50:53], v160 offset:224
	ds_read_b128 v[56:59], v160 offset:192
	ds_read_b128 v[162:165], v160 offset:128
	ds_read_b128 v[166:169], v160 offset:160
	s_waitcnt lgkmcnt(3)
	v_sub_f32_e32 v51, v99, v51
	v_sub_f32_e32 v50, v98, v50
	s_waitcnt lgkmcnt(2)
	v_sub_f32_e32 v55, v97, v59
	v_sub_f32_e32 v54, v96, v58
	v_sub_f32_e32 v59, v95, v57
	v_sub_f32_e32 v60, v94, v56
	s_waitcnt lgkmcnt(0)
	v_sub_f32_e32 v67, v91, v167
	v_sub_f32_e32 v65, v93, v169
	v_sub_f32_e32 v62, v92, v168
	v_sub_f32_e32 v64, v90, v166
	v_sub_f32_e32 v85, v89, v165
	v_sub_f32_e32 v84, v88, v164
	v_sub_f32_e32 v87, v87, v163
	v_sub_f32_e32 v86, v86, v162
	ds_read_b128 v[88:91], v160 offset:96
	ds_read_b128 v[92:95], v160 offset:64
	ds_read_b128 v[96:99], v160
	ds_read_b128 v[162:165], v160 offset:32
	v_sub_f32_e32 v49, v101, v53
	v_sub_f32_e32 v48, v100, v52
	s_waitcnt lgkmcnt(3)
	v_sub_f32_e32 v53, v83, v91
	v_sub_f32_e32 v52, v82, v90
	v_sub_f32_e32 v57, v81, v89
	v_sub_f32_e32 v56, v80, v88
	s_waitcnt lgkmcnt(2)
	v_sub_f32_e32 v61, v79, v95
	v_sub_f32_e32 v58, v78, v94
	v_sub_f32_e32 v63, v77, v93
	v_sub_f32_e32 v66, v76, v92
	s_waitcnt lgkmcnt(0)
	v_sub_f32_e32 v75, v75, v165
	v_sub_f32_e32 v74, v74, v164
	v_sub_f32_e32 v73, v73, v163
	v_sub_f32_e32 v72, v72, v162
	v_sub_f32_e32 v71, v71, v99
	v_sub_f32_e32 v70, v70, v98
	v_sub_f32_e32 v69, v69, v97
	v_sub_f32_e32 v68, v68, v96
	s_cmp_lt_i32 s34, s42
	s_cbranch_scc1 .Lfx0_exp
	v_add_u32_e32 v76, 2, v159
	v_cmp_le_i32_e32 vcc, v76, v128
	v_cmp_le_i32_e64 s[8:9], v159, v118
	v_add_u32_e32 v76, 3, v159
	v_cndmask_b32_e32 v70, v127, v70, vcc
	v_cmp_le_i32_e32 vcc, v159, v133
	v_cndmask_b32_e64 v86, v127, v86, s[8:9]
	v_cmp_lt_i32_e64 s[8:9], v159, v128
	v_cndmask_b32_e32 v84, v127, v84, vcc
	v_cmp_le_i32_e32 vcc, v159, v134
	v_cndmask_b32_e64 v69, v127, v69, s[8:9]
	v_cmp_le_i32_e64 s[8:9], v159, v128
	v_cndmask_b32_e32 v85, v127, v85, vcc
	v_cmp_le_i32_e32 vcc, v159, v135
	v_cmp_le_i32_e64 s[6:7], v76, v128
	v_cndmask_b32_e64 v68, v127, v68, s[8:9]
	v_cndmask_b32_e32 v72, v127, v72, vcc
	v_cmp_le_i32_e32 vcc, v159, v136
	v_cmp_le_i32_e64 s[8:9], v159, v132
	v_cndmask_b32_e64 v71, v127, v71, s[6:7]
	v_cndmask_b32_e32 v64, v127, v64, vcc
	v_cmp_le_i32_e32 vcc, v159, v137
	v_cndmask_b32_e64 v87, v127, v87, s[8:9]
	s_nop 0
	v_cndmask_b32_e32 v73, v127, v73, vcc
	v_cmp_le_i32_e32 vcc, v159, v138
	s_nop 1
	v_cndmask_b32_e32 v67, v127, v67, vcc
	v_cmp_le_i32_e32 vcc, v159, v139
	s_nop 1
	v_cndmask_b32_e32 v74, v127, v74, vcc
	v_cmp_le_i32_e32 vcc, v159, v140
	s_nop 1
	v_cndmask_b32_e32 v62, v127, v62, vcc
	v_cmp_le_i32_e32 vcc, v159, v141
	s_nop 1
	v_cndmask_b32_e32 v75, v127, v75, vcc
	v_cmp_le_i32_e32 vcc, v159, v142
	s_nop 1
	v_cndmask_b32_e32 v65, v127, v65, vcc
	v_cmp_le_i32_e32 vcc, v159, v143
	s_nop 1
	v_cndmask_b32_e32 v66, v127, v66, vcc
	v_cmp_le_i32_e32 vcc, v159, v144
	s_nop 1
	v_cndmask_b32_e32 v60, v127, v60, vcc
	v_cmp_le_i32_e32 vcc, v159, v145
	s_nop 1
	v_cndmask_b32_e32 v63, v127, v63, vcc
	v_cmp_le_i32_e32 vcc, v159, v146
	s_nop 1
	v_cndmask_b32_e32 v59, v127, v59, vcc
	v_cmp_le_i32_e32 vcc, v159, v147
	s_nop 1
	v_cndmask_b32_e32 v58, v127, v58, vcc
	v_cmp_le_i32_e32 vcc, v159, v148
	s_nop 1
	v_cndmask_b32_e32 v54, v127, v54, vcc
	v_cmp_le_i32_e32 vcc, v159, v149
	s_nop 1
	v_cndmask_b32_e32 v61, v127, v61, vcc
	v_cmp_le_i32_e32 vcc, v159, v150
	s_nop 1
	v_cndmask_b32_e32 v55, v127, v55, vcc
	v_cmp_le_i32_e32 vcc, v159, v151
	s_nop 1
	v_cndmask_b32_e32 v56, v127, v56, vcc
	v_cmp_le_i32_e32 vcc, v159, v152
	s_nop 1
	v_cndmask_b32_e32 v50, v127, v50, vcc
	v_cmp_le_i32_e32 vcc, v159, v153
	s_nop 1
	v_cndmask_b32_e32 v57, v127, v57, vcc
	v_cmp_le_i32_e32 vcc, v159, v154
	s_nop 1
	v_cndmask_b32_e32 v51, v127, v51, vcc
	v_cmp_le_i32_e32 vcc, v159, v155
	s_nop 1
	v_cndmask_b32_e32 v52, v127, v52, vcc
	v_cmp_le_i32_e32 vcc, v159, v156
	s_nop 1
	v_cndmask_b32_e32 v48, v127, v48, vcc
	v_cmp_le_i32_e32 vcc, v159, v157
	s_nop 1
	v_cndmask_b32_e32 v53, v127, v53, vcc
	v_cmp_le_i32_e32 vcc, v159, v158
	s_nop 1
	v_cndmask_b32_e32 v49, v127, v49, vcc
.Lfx0_exp:
	v_exp_f32_e32 v68, v68
	v_exp_f32_e32 v76, v86
	v_exp_f32_e32 v69, v69
	v_exp_f32_e32 v77, v87
	v_exp_f32_e32 v70, v70
	v_exp_f32_e32 v78, v84
	v_exp_f32_e32 v71, v71
	v_exp_f32_e32 v79, v85
	v_exp_f32_e32 v72, v72
	v_exp_f32_e32 v64, v64
	v_add_f32_e32 v80, v76, v68
	v_exp_f32_e32 v73, v73
	v_exp_f32_e32 v67, v67
	v_add_f32_e32 v80, 0, v80
	v_add_f32_e32 v81, v77, v69
	v_exp_f32_e32 v74, v74
	v_exp_f32_e32 v62, v62
	v_add_f32_e32 v80, v81, v80
	v_add_f32_e32 v81, v78, v70
	v_exp_f32_e32 v75, v75
	v_exp_f32_e32 v65, v65
	v_add_f32_e32 v80, v81, v80
	v_add_f32_e32 v81, v79, v71
	v_exp_f32_e32 v66, v66
	v_exp_f32_e32 v60, v60
	v_add_f32_e32 v80, v81, v80
	v_add_f32_e32 v81, v64, v72
	v_add_f32_e32 v80, v81, v80
	v_add_f32_e32 v81, v67, v73
	v_exp_f32_e32 v63, v63
	v_exp_f32_e32 v82, v59
	v_add_f32_e32 v80, v81, v80
	v_add_f32_e32 v81, v62, v74
	v_add_f32_e32 v80, v81, v80
	v_add_f32_e32 v81, v65, v75
	v_add_f32_e32 v59, v81, v80
	v_add_f32_e32 v80, v60, v66
	v_exp_f32_e32 v81, v58
	v_exp_f32_e32 v83, v54
	v_add_f32_e32 v59, v80, v59
	v_add_f32_e32 v80, v82, v63
	v_exp_f32_e32 v54, v61
	v_exp_f32_e32 v61, v55
	v_add_f32_e32 v55, v80, v59
	v_exp_f32_e32 v80, v56
	v_exp_f32_e32 v84, v50
	v_exp_f32_e32 v50, v57
	v_exp_f32_e32 v85, v51
	v_add_f32_e32 v58, v83, v81
	v_exp_f32_e32 v86, v52
	v_exp_f32_e32 v87, v48
	v_add_f32_e32 v55, v58, v55
	v_add_f32_e32 v58, v61, v54
	v_exp_f32_e32 v48, v53
	v_exp_f32_e32 v88, v49
	v_add_f32_e32 v51, v58, v55
	v_add_f32_e32 v55, v84, v80
	v_add_f32_e32 v51, v55, v51
	v_add_f32_e32 v55, v85, v50
	v_add_f32_e32 v49, v55, v51
	v_add_f32_e32 v51, v87, v86
	v_add_f32_e32 v49, v51, v49
	v_add_f32_e32 v51, v88, v48
	v_add_f32_e32 v49, v51, v49
	v_add_f32_e32 v130, v130, v49
	v_cvt_pk_bf16_f32 v56, v68, v69
	v_cvt_pk_bf16_f32 v57, v70, v71
	v_cvt_pk_bf16_f32 v58, v72, v73
	v_cvt_pk_bf16_f32 v59, v74, v75
	v_cvt_pk_bf16_f32 v52, v66, v63
	v_cvt_pk_bf16_f32 v53, v81, v54
	v_cvt_pk_bf16_f32 v54, v80, v50
	v_cvt_pk_bf16_f32 v55, v86, v48
	v_cvt_pk_bf16_f32 v48, v76, v77
	v_cvt_pk_bf16_f32 v49, v78, v79
	v_cvt_pk_bf16_f32 v50, v64, v67
	v_cvt_pk_bf16_f32 v51, v62, v65
	v_cvt_pk_bf16_f32 v62, v60, v82
	v_cvt_pk_bf16_f32 v63, v83, v61
	v_cvt_pk_bf16_f32 v64, v84, v85
	v_cvt_pk_bf16_f32 v65, v87, v88
	v_lshl_add_u64 v[122:123], v[122:123], 0, s[28:29]
	v_subrev_u32_e32 v159, 64, v159
	v_add_u32_e32 v160, 0xffffff00, v160
	s_add_i32 s35, s35, 1
	s_add_i32 s34, s34, -1
	s_cmp_gt_i32 s55, 1
	s_cbranch_scc1 .Lfx0_w2
	s_cmp_lg_u32 s55, 1
	s_cbranch_scc1 .Lfx0_w0
	s_waitcnt vmcnt(1) lgkmcnt(0)
	s_barrier
	s_branch .Lfx0_bdone

; template <int MODE> __device__ __forceinline__ void attn_unit(int b, int h, int qb, int t_lo, const bf16_t* Q, const bf16_t* __restrict__ K, const bf16_t* __restrict__ V, bf16_t* O, ATT_LAS unsigned char* lds, const int wid, const float kn2, const float bmax) {
;     ...
; #pragma unroll 1
;     for (int j = 0; j < n - 1; ++j) ATT_ITER(j, true, true);
.Lfx0_bdone:
	s_cmp_ge_i32 s35, s12
	s_cbranch_scc1 .LBB0_418
	s_mov_b32 s6, s54
	s_add_i32 s7, s35, 4
	s_cmp_ge_i32 s7, s43
	s_mov_b32 s55, 0
	s_cbranch_scc0 .LBB0_396
	s_branch .LBB0_397

; #define ATT_LAS __attribute__((address_space(3)))
; #define ATT_MFMA(a, b, c) __builtin_amdgcn_mfma_f32_32x32x16_bf16((a), (b), (c), 0, 0, 0)
; __device__ __forceinline__ void qkt(f32x16& p0, f32x16& p1, lds_cptr kb, const bf16x8* qr, const f32x16& z) {
; #pragma unroll
;     for (int d0 = 0; d0 < 4; ++d0) {
;         const bf16x8 b0 = *(const ATT_LAS bf16x8*)(kb + d0 * 2048);
;         const bf16x8 b1 = *(const ATT_LAS bf16x8*)(kb + d0 * 2048 + 512);
;         if (d0 == 0) { p0 = ATT_MFMA(b0, qr[0], z); p1 = ATT_MFMA(b1, qr[0], z); }
;         else { p0 = ATT_MFMA(b0, qr[d0], p0); p1 = ATT_MFMA(b1, qr[d0], p1); } }
; }
; __device__ __forceinline__ void pv(f32x16* o, int vb, bf16x8 pa0, bf16x8 pa1, bf16x8 pa2, bf16x8 pa3) {
; #pragma unroll
;     for (int d0 = 0; d0 < 2; ++d0) { s16x4 lo[4], hi[4];
; #pragma unroll
;         for (int ks = 0; ks < 4; ++ks) {
;             asm volatile("ds_read_b64_tr_b16 %0,%1 offset:%c2" : "=&v"(lo[ks]) : "v"(vb), "i"(d0 * 4096 + ks * 1024) : "memory");
;             asm volatile("ds_read_b64_tr_b16 %0,%1 offset:%c2" : "=&v"(hi[ks]) : "v"(vb), "i"(d0 * 4096 + ks * 1024 + 512) : "memory"); }
;         asm volatile("s_waitcnt lgkmcnt(0)" ::: "memory"); __builtin_amdgcn_sched_barrier(0);
;     ...
;         o[d0] = ATT_MFMA(pa0, ATT_PK(0), o[d0]);
;         o[d0] = ATT_MFMA(pa1, ATT_PK(1), o[d0]);
;         o[d0] = ATT_MFMA(pa2, ATT_PK(2), o[d0]);
;         o[d0] = ATT_MFMA(pa3, ATT_PK(3), o[d0]);
;     ...
;     }
; }
.LBB0_1723:
	s_add_i32 s60, s10, 0x2000
	s_and_b32 s11, s60, 0x6000
	v_add_u32_e32 v60, s11, v129
	s_and_b32 s10, s10, 0x6000
	ds_read_b128 v[210:213], v60
	ds_read_b128 v[214:217], v60 offset:512
	ds_read_b128 v[218:221], v60 offset:2048
	ds_read_b128 v[222:225], v60 offset:2560
	ds_read_b128 v[226:229], v60 offset:4096
	ds_read_b128 v[230:233], v60 offset:4608
	ds_read_b128 v[234:237], v60 offset:6144
	ds_read_b128 v[238:241], v60 offset:6656
	v_add_u32_e32 v242, s10, v131
	ds_read_b64_tr_b16 v[178:179], v242
	ds_read_b64_tr_b16 v[180:181], v242 offset:512
	ds_read_b64_tr_b16 v[182:183], v242 offset:1024
	ds_read_b64_tr_b16 v[184:185], v242 offset:1536
	ds_read_b64_tr_b16 v[186:187], v242 offset:2048
	ds_read_b64_tr_b16 v[188:189], v242 offset:2560
	ds_read_b64_tr_b16 v[190:191], v242 offset:3072
	ds_read_b64_tr_b16 v[192:193], v242 offset:3584
	s_waitcnt lgkmcnt(14)
	v_mfma_f32_32x32x16_bf16 v[68:83], v[210:213], v[114:117], v[0:15]
	v_mfma_f32_32x32x16_bf16 v[86:101], v[214:217], v[114:117], v[0:15]
	s_waitcnt lgkmcnt(12)
	v_mfma_f32_32x32x16_bf16 v[68:83], v[218:221], v[110:113], v[68:83]
	v_mfma_f32_32x32x16_bf16 v[86:101], v[222:225], v[110:113], v[86:101]
	s_waitcnt lgkmcnt(10)
	v_mfma_f32_32x32x16_bf16 v[68:83], v[226:229], v[106:109], v[68:83]
	v_mfma_f32_32x32x16_bf16 v[86:101], v[230:233], v[106:109], v[86:101]
	s_waitcnt lgkmcnt(8)
	v_mfma_f32_32x32x16_bf16 v[68:83], v[234:237], v[102:105], v[68:83]
	v_mfma_f32_32x32x16_bf16 v[86:101], v[238:241], v[102:105], v[86:101]
	ds_read_b64_tr_b16 v[194:195], v242 offset:4096
	ds_read_b64_tr_b16 v[196:197], v242 offset:4608
	ds_read_b64_tr_b16 v[198:199], v242 offset:5120
	ds_read_b64_tr_b16 v[200:201], v242 offset:5632
	ds_read_b64_tr_b16 v[202:203], v242 offset:6144
	ds_read_b64_tr_b16 v[204:205], v242 offset:6656
	ds_read_b64_tr_b16 v[206:207], v242 offset:7168
	ds_read_b64_tr_b16 v[208:209], v242 offset:7680
	s_waitcnt lgkmcnt(14)
	v_mfma_f32_32x32x16_bf16 v[16:31], v[56:59], v[178:181], v[16:31]
	s_waitcnt lgkmcnt(12)
	v_mfma_f32_32x32x16_bf16 v[16:31], v[52:55], v[182:185], v[16:31]
	s_waitcnt lgkmcnt(10)
	v_mfma_f32_32x32x16_bf16 v[16:31], v[48:51], v[186:189], v[16:31]
	s_waitcnt lgkmcnt(8)
	v_mfma_f32_32x32x16_bf16 v[16:31], v[62:65], v[190:193], v[16:31]
	s_waitcnt lgkmcnt(6)
	v_mfma_f32_32x32x16_bf16 v[32:47], v[56:59], v[194:197], v[32:47]
	s_waitcnt lgkmcnt(4)
	v_mfma_f32_32x32x16_bf16 v[32:47], v[52:55], v[198:201], v[32:47]
	s_waitcnt lgkmcnt(2)
	v_mfma_f32_32x32x16_bf16 v[32:47], v[48:51], v[202:205], v[32:47]
	s_waitcnt lgkmcnt(0)
	v_mfma_f32_32x32x16_bf16 v[32:47], v[62:65], v[206:209], v[32:47]
	s_barrier
	ds_read_b128 v[50:53], v160 offset:224
	ds_read_b128 v[56:59], v160 offset:192
	ds_read_b128 v[162:165], v160 offset:128
	ds_read_b128 v[166:169], v160 offset:160
	s_waitcnt lgkmcnt(3)
	v_sub_f32_e32 v51, v99, v51
	v_sub_f32_e32 v50, v98, v50
	s_waitcnt lgkmcnt(2)
	v_sub_f32_e32 v55, v97, v59
	v_sub_f32_e32 v54, v96, v58
	v_sub_f32_e32 v59, v95, v57
	v_sub_f32_e32 v60, v94, v56
	s_waitcnt lgkmcnt(0)
	v_sub_f32_e32 v67, v91, v167
	v_sub_f32_e32 v65, v93, v169
	v_sub_f32_e32 v62, v92, v168
	v_sub_f32_e32 v64, v90, v166
	v_sub_f32_e32 v85, v89, v165
	v_sub_f32_e32 v84, v88, v164
	v_sub_f32_e32 v87, v87, v163
	v_sub_f32_e32 v86, v86, v162
	ds_read_b128 v[88:91], v160 offset:96
	ds_read_b128 v[92:95], v160 offset:64
	ds_read_b128 v[96:99], v160
	ds_read_b128 v[162:165], v160 offset:32
	v_sub_f32_e32 v49, v101, v53
	v_sub_f32_e32 v48, v100, v52
	s_waitcnt lgkmcnt(3)
	v_sub_f32_e32 v53, v83, v91
	v_sub_f32_e32 v52, v82, v90
	v_sub_f32_e32 v57, v81, v89
	v_sub_f32_e32 v56, v80, v88
	s_waitcnt lgkmcnt(2)
	v_sub_f32_e32 v61, v79, v95
	v_sub_f32_e32 v58, v78, v94
	v_sub_f32_e32 v63, v77, v93
	v_sub_f32_e32 v66, v76, v92
	s_waitcnt lgkmcnt(0)
	v_sub_f32_e32 v75, v75, v165
	v_sub_f32_e32 v74, v74, v164
	v_sub_f32_e32 v73, v73, v163
	v_sub_f32_e32 v72, v72, v162
	v_sub_f32_e32 v71, v71, v99
	v_sub_f32_e32 v70, v70, v98
	v_sub_f32_e32 v69, v69, v97
	v_sub_f32_e32 v68, v68, v96
	s_cmp_lt_i32 s45, s42
	s_cbranch_scc1 .Lfx2_exp
	v_add_u32_e32 v76, 2, v159
	v_cmp_le_i32_e32 vcc, v76, v128
	v_cmp_le_i32_e64 s[12:13], v159, v118
	v_add_u32_e32 v76, 3, v159
	v_cndmask_b32_e32 v70, v127, v70, vcc
	v_cmp_le_i32_e32 vcc, v159, v133
	v_cndmask_b32_e64 v86, v127, v86, s[12:13]
	v_cmp_lt_i32_e64 s[12:13], v159, v128
	v_cndmask_b32_e32 v84, v127, v84, vcc
	v_cmp_le_i32_e32 vcc, v159, v134
	v_cndmask_b32_e64 v69, v127, v69, s[12:13]
	v_cmp_le_i32_e64 s[12:13], v159, v128
	v_cndmask_b32_e32 v85, v127, v85, vcc
	v_cmp_le_i32_e32 vcc, v159, v135
	v_cmp_le_i32_e64 s[10:11], v76, v128
	v_cndmask_b32_e64 v68, v127, v68, s[12:13]
	v_cndmask_b32_e32 v72, v127, v72, vcc
	v_cmp_le_i32_e32 vcc, v159, v136
	v_cmp_le_i32_e64 s[12:13], v159, v132
	v_cndmask_b32_e64 v71, v127, v71, s[10:11]
	v_cndmask_b32_e32 v64, v127, v64, vcc
	v_cmp_le_i32_e32 vcc, v159, v137
	v_cndmask_b32_e64 v87, v127, v87, s[12:13]
	s_nop 0
	v_cndmask_b32_e32 v73, v127, v73, vcc
	v_cmp_le_i32_e32 vcc, v159, v138
	s_nop 1
	v_cndmask_b32_e32 v67, v127, v67, vcc
	v_cmp_le_i32_e32 vcc, v159, v139
	s_nop 1
	v_cndmask_b32_e32 v74, v127, v74, vcc
	v_cmp_le_i32_e32 vcc, v159, v140
	s_nop 1
	v_cndmask_b32_e32 v62, v127, v62, vcc
	v_cmp_le_i32_e32 vcc, v159, v141
	s_nop 1
	v_cndmask_b32_e32 v75, v127, v75, vcc
	v_cmp_le_i32_e32 vcc, v159, v142
	s_nop 1
	v_cndmask_b32_e32 v65, v127, v65, vcc
	v_cmp_le_i32_e32 vcc, v159, v143
	s_nop 1
	v_cndmask_b32_e32 v66, v127, v66, vcc
	v_cmp_le_i32_e32 vcc, v159, v144
	s_nop 1
	v_cndmask_b32_e32 v60, v127, v60, vcc
	v_cmp_le_i32_e32 vcc, v159, v145
	s_nop 1
	v_cndmask_b32_e32 v63, v127, v63, vcc
	v_cmp_le_i32_e32 vcc, v159, v146
	s_nop 1
	v_cndmask_b32_e32 v59, v127, v59, vcc
	v_cmp_le_i32_e32 vcc, v159, v147
	s_nop 1
	v_cndmask_b32_e32 v58, v127, v58, vcc
	v_cmp_le_i32_e32 vcc, v159, v148
	s_nop 1
	v_cndmask_b32_e32 v54, v127, v54, vcc
	v_cmp_le_i32_e32 vcc, v159, v149
	s_nop 1
	v_cndmask_b32_e32 v61, v127, v61, vcc
	v_cmp_le_i32_e32 vcc, v159, v150
	s_nop 1
	v_cndmask_b32_e32 v55, v127, v55, vcc
	v_cmp_le_i32_e32 vcc, v159, v151
	s_nop 1
	v_cndmask_b32_e32 v56, v127, v56, vcc
	v_cmp_le_i32_e32 vcc, v159, v152
	s_nop 1
	v_cndmask_b32_e32 v50, v127, v50, vcc
	v_cmp_le_i32_e32 vcc, v159, v153
	s_nop 1
	v_cndmask_b32_e32 v57, v127, v57, vcc
	v_cmp_le_i32_e32 vcc, v159, v154
	s_nop 1
	v_cndmask_b32_e32 v51, v127, v51, vcc
	v_cmp_le_i32_e32 vcc, v159, v155
	s_nop 1
	v_cndmask_b32_e32 v52, v127, v52, vcc
	v_cmp_le_i32_e32 vcc, v159, v156
	s_nop 1
	v_cndmask_b32_e32 v48, v127, v48, vcc
	v_cmp_le_i32_e32 vcc, v159, v157
	s_nop 1
	v_cndmask_b32_e32 v53, v127, v53, vcc
	v_cmp_le_i32_e32 vcc, v159, v158
	s_nop 1
	v_cndmask_b32_e32 v49, v127, v49, vcc
.Lfx2_exp:
	v_exp_f32_e32 v68, v68
	v_exp_f32_e32 v76, v86
	v_exp_f32_e32 v69, v69
	v_exp_f32_e32 v77, v87
	v_exp_f32_e32 v70, v70
	v_exp_f32_e32 v78, v84
	v_exp_f32_e32 v71, v71
	v_exp_f32_e32 v79, v85
	v_exp_f32_e32 v72, v72
	v_exp_f32_e32 v64, v64
	v_add_f32_e32 v80, v76, v68
	v_exp_f32_e32 v73, v73
	v_exp_f32_e32 v67, v67
	v_add_f32_e32 v80, 0, v80
	v_add_f32_e32 v81, v77, v69
	v_exp_f32_e32 v74, v74
	v_exp_f32_e32 v62, v62
	v_add_f32_e32 v80, v81, v80
	v_add_f32_e32 v81, v78, v70
	v_exp_f32_e32 v75, v75
	v_exp_f32_e32 v65, v65
	v_add_f32_e32 v80, v81, v80
	v_add_f32_e32 v81, v79, v71
	v_exp_f32_e32 v66, v66
	v_exp_f32_e32 v60, v60
	v_add_f32_e32 v80, v81, v80
	v_add_f32_e32 v81, v64, v72
	v_add_f32_e32 v80, v81, v80
	v_add_f32_e32 v81, v67, v73
	v_exp_f32_e32 v63, v63
	v_exp_f32_e32 v82, v59
	v_add_f32_e32 v80, v81, v80
	v_add_f32_e32 v81, v62, v74
	v_add_f32_e32 v80, v81, v80
	v_add_f32_e32 v81, v65, v75
	v_add_f32_e32 v59, v81, v80
	v_add_f32_e32 v80, v60, v66
	v_exp_f32_e32 v81, v58
	v_exp_f32_e32 v83, v54
	v_add_f32_e32 v59, v80, v59
	v_add_f32_e32 v80, v82, v63
	v_exp_f32_e32 v54, v61
	v_exp_f32_e32 v61, v55
	v_add_f32_e32 v55, v80, v59
	v_exp_f32_e32 v80, v56
	v_exp_f32_e32 v84, v50
	v_exp_f32_e32 v50, v57
	v_exp_f32_e32 v85, v51
	v_add_f32_e32 v58, v83, v81
	v_exp_f32_e32 v86, v52
	v_exp_f32_e32 v87, v48
	v_add_f32_e32 v55, v58, v55
	v_add_f32_e32 v58, v61, v54
	v_exp_f32_e32 v48, v53
	v_exp_f32_e32 v88, v49
	v_add_f32_e32 v51, v58, v55
	v_add_f32_e32 v55, v84, v80
	v_add_f32_e32 v51, v55, v51
	v_add_f32_e32 v55, v85, v50
	v_add_f32_e32 v49, v55, v51
	v_add_f32_e32 v51, v87, v86
	v_add_f32_e32 v49, v51, v49
	v_add_f32_e32 v51, v88, v48
	v_add_f32_e32 v49, v51, v49
	v_add_f32_e32 v130, v130, v49
	v_cvt_pk_bf16_f32 v56, v68, v69
	v_cvt_pk_bf16_f32 v57, v70, v71
	v_cvt_pk_bf16_f32 v58, v72, v73
	v_cvt_pk_bf16_f32 v59, v74, v75
	v_cvt_pk_bf16_f32 v52, v66, v63
	v_cvt_pk_bf16_f32 v53, v81, v54
	v_cvt_pk_bf16_f32 v54, v80, v50
	v_cvt_pk_bf16_f32 v55, v86, v48
	v_cvt_pk_bf16_f32 v48, v76, v77
	v_cvt_pk_bf16_f32 v49, v78, v79
	v_cvt_pk_bf16_f32 v50, v64, v67
	v_cvt_pk_bf16_f32 v51, v62, v65
	v_cvt_pk_bf16_f32 v62, v60, v82
	v_cvt_pk_bf16_f32 v63, v83, v61
	v_cvt_pk_bf16_f32 v64, v84, v85
	v_cvt_pk_bf16_f32 v65, v87, v88
	v_lshl_add_u64 v[122:123], v[122:123], 0, s[34:35]
	v_subrev_u32_e32 v159, 64, v159
	v_add_u32_e32 v160, 0xffffff00, v160
	s_add_i32 s43, s43, 1
	s_add_i32 s45, s45, -1
	s_cmp_gt_i32 s61, 1
	s_cbranch_scc1 .Lfx2_w2
	s_cmp_lg_u32 s61, 1
	s_cbranch_scc1 .Lfx2_w0
	s_waitcnt vmcnt(1) lgkmcnt(0)
	s_barrier
	s_branch .Lfx2_bdone

; template <int MODE> __device__ __forceinline__ void attn_unit(int b, int h, int qb, int t_lo, const bf16_t* Q, const bf16_t* __restrict__ K, const bf16_t* __restrict__ V, bf16_t* O, ATT_LAS unsigned char* lds, const int wid, const float kn2, const float bmax) {
;     ...
; #pragma unroll 1
;     for (int j = 0; j < n - 1; ++j) ATT_ITER(j, true, true);
.Lfx2_bdone:
	s_cmp_ge_i32 s43, s44
	s_cbranch_scc1 .LBB0_1742
	s_mov_b32 s10, s60
	s_add_i32 s11, s43, 4
	s_cmp_ge_i32 s11, s21
	s_mov_b32 s61, 0
	s_cbranch_scc0 .LBB0_1720
	s_branch .LBB0_1721
